# in-proj epilogue Z stores write-through (sc1) so the grid barrier release fence has less dirty L2 to flush
# speedup vs baseline: 1.0015x; 1.0015x over previous
.LBB0_478:
	s_lshl_b32 s15, s54, 8
	s_add_i32 s15, s15, s88
	v_or_b32_e32 v152, s15, v148
	v_lshl_or_b32 v144, s95, 8, v150
	s_cmp_gt_i32 s95, 1
	v_mov_b64_e32 v[146:147], s[8:9]
	v_ashrrev_i32_e32 v145, 31, v144
	s_cselect_b64 s[52:53], -1, 0
	v_mad_i64_i32 v[146:147], s[6:7], v152, s97, v[146:147]
	v_lshl_add_u64 v[146:147], v[144:145], 1, v[146:147]
	s_mov_b64 s[6:7], -1
	s_and_b64 vcc, exec, s[52:53]
	v_cvt_pk_bf16_f32 v126, v126, v127
	v_cvt_pk_bf16_f32 v127, v128, v129
	v_cvt_pk_bf16_f32 v128, v122, v123
	v_cvt_pk_bf16_f32 v129, v124, v125
	s_cbranch_vccz .LBB0_480
	global_store_dwordx4 v[146:147], v[126:129], off sc1
	s_mov_b64 s[6:7], 0
.LBB0_480:
	v_lshlrev_b32_e32 v32, 4, v152
	s_ashr_i32 s15, s15, 6
	v_and_b32_e32 v32, 0x7cf0, v32
	s_andn2_b32 s15, s15, 31
	s_andn2_b64 vcc, exec, s[6:7]
	v_ashrrev_i32_e32 v124, 4, v144
	v_lshlrev_b32_e32 v32, 1, v32
	v_lshlrev_b32_e32 v122, 1, v138
	s_cbranch_vccnz .LBB0_482
	v_add_u32_e32 v154, s15, v124
	v_ashrrev_i32_e32 v155, 31, v154
	v_lshlrev_b64 v[154:155], 16, v[154:155]
	v_lshl_add_u64 v[154:155], s[10:11], 0, v[154:155]
	v_lshl_add_u64 v[154:155], v[154:155], 0, v[32:33]
	v_mov_b32_e32 v123, v33
	v_lshl_add_u64 v[154:155], v[154:155], 0, v[122:123]
	global_store_dwordx4 v[154:155], v[126:129], off sc1

.LBB0_488:
	v_or_b32_e32 v32, 16, v152
	v_mov_b64_e32 v[114:115], s[8:9]
	v_mad_i64_i32 v[114:115], s[52:53], v32, s97, v[114:115]
	v_lshl_add_u64 v[114:115], v[144:145], 1, v[114:115]
	s_and_b64 vcc, exec, s[6:7]
	s_mov_b64 s[52:53], -1
	v_cvt_pk_bf16_f32 v110, v110, v111
	v_cvt_pk_bf16_f32 v111, v112, v113
	v_cvt_pk_bf16_f32 v112, v106, v107
	v_cvt_pk_bf16_f32 v113, v108, v109
	s_cbranch_vccnz .LBB0_490
	s_mov_b64 s[52:53], 0
	global_store_dwordx4 v[114:115], v[110:113], off sc1
.LBB0_490:
	v_lshlrev_b32_e32 v32, 4, v32
	v_and_b32_e32 v32, 0x7df0, v32
	s_andn2_b64 vcc, exec, s[52:53]
	v_lshlrev_b32_e32 v32, 1, v32
	s_cbranch_vccnz .LBB0_492
	v_add_u32_e32 v106, s15, v124
	v_ashrrev_i32_e32 v107, 31, v106
	v_lshlrev_b64 v[106:107], 16, v[106:107]
	v_lshl_add_u64 v[106:107], s[10:11], 0, v[106:107]
	v_lshl_add_u64 v[106:107], v[106:107], 0, v[32:33]
	v_mov_b32_e32 v123, v33
	v_lshl_add_u64 v[106:107], v[106:107], 0, v[122:123]
	global_store_dwordx4 v[106:107], v[110:113], off sc1

.LBB0_498:
	v_or_b32_e32 v32, 32, v152
	v_mov_b64_e32 v[98:99], s[8:9]
	v_mad_i64_i32 v[98:99], s[52:53], v32, s97, v[98:99]
	v_lshl_add_u64 v[98:99], v[144:145], 1, v[98:99]
	s_and_b64 vcc, exec, s[6:7]
	s_mov_b64 s[52:53], -1
	v_cvt_pk_bf16_f32 v94, v94, v95
	v_cvt_pk_bf16_f32 v95, v96, v97
	v_cvt_pk_bf16_f32 v96, v90, v91
	v_cvt_pk_bf16_f32 v97, v92, v93
	s_cbranch_vccnz .LBB0_500
	s_mov_b64 s[52:53], 0
	global_store_dwordx4 v[98:99], v[94:97], off sc1
.LBB0_500:
	v_lshlrev_b32_e32 v32, 4, v32
	v_and_b32_e32 v32, 0x7ef0, v32
	s_andn2_b64 vcc, exec, s[52:53]
	v_lshlrev_b32_e32 v32, 1, v32
	s_cbranch_vccnz .LBB0_502
	v_add_u32_e32 v90, s15, v124
	v_ashrrev_i32_e32 v91, 31, v90
	v_lshlrev_b64 v[90:91], 16, v[90:91]
	v_lshl_add_u64 v[90:91], s[10:11], 0, v[90:91]
	v_lshl_add_u64 v[90:91], v[90:91], 0, v[32:33]
	v_mov_b32_e32 v123, v33
	v_lshl_add_u64 v[90:91], v[90:91], 0, v[122:123]
	global_store_dwordx4 v[90:91], v[94:97], off sc1

.LBB0_508:
	v_or_b32_e32 v32, 48, v152
	v_mov_b64_e32 v[82:83], s[8:9]
	v_mad_i64_i32 v[82:83], s[52:53], v32, s97, v[82:83]
	v_lshl_add_u64 v[82:83], v[144:145], 1, v[82:83]
	s_and_b64 vcc, exec, s[6:7]
	s_mov_b64 s[52:53], -1
	v_cvt_pk_bf16_f32 v78, v78, v79
	v_cvt_pk_bf16_f32 v79, v80, v81
	v_cvt_pk_bf16_f32 v80, v74, v75
	v_cvt_pk_bf16_f32 v81, v76, v77
	s_cbranch_vccnz .LBB0_510
	s_mov_b64 s[52:53], 0
	global_store_dwordx4 v[82:83], v[78:81], off sc1
.LBB0_510:
	v_lshlrev_b32_e32 v32, 4, v32
	v_and_b32_e32 v32, 0x7ff0, v32
	s_andn2_b64 vcc, exec, s[52:53]
	v_lshlrev_b32_e32 v32, 1, v32
	s_cbranch_vccnz .LBB0_512
	v_add_u32_e32 v74, s15, v124
	v_ashrrev_i32_e32 v75, 31, v74
	v_lshlrev_b64 v[74:75], 16, v[74:75]
	v_lshl_add_u64 v[74:75], s[10:11], 0, v[74:75]
	v_lshl_add_u64 v[74:75], v[74:75], 0, v[32:33]
	v_mov_b32_e32 v123, v33
	v_lshl_add_u64 v[74:75], v[74:75], 0, v[122:123]
	global_store_dwordx4 v[74:75], v[78:81], off sc1

.LBB0_518:
	v_add_u32_e32 v32, 0x80, v152
	v_mov_b64_e32 v[66:67], s[8:9]
	v_mad_i64_i32 v[66:67], s[52:53], v32, s97, v[66:67]
	v_lshl_add_u64 v[66:67], v[144:145], 1, v[66:67]
	s_and_b64 vcc, exec, s[6:7]
	s_mov_b64 s[52:53], -1
	v_cvt_pk_bf16_f32 v62, v62, v63
	v_cvt_pk_bf16_f32 v63, v64, v65
	v_cvt_pk_bf16_f32 v64, v58, v59
	v_cvt_pk_bf16_f32 v65, v60, v61
	s_cbranch_vccnz .LBB0_520
	s_mov_b64 s[52:53], 0
	global_store_dwordx4 v[66:67], v[62:65], off sc1
.LBB0_520:
	v_ashrrev_i32_e32 v58, 6, v32
	v_lshlrev_b32_e32 v32, 4, v32
	v_and_b32_e32 v32, 0x7cf0, v32
	v_and_b32_e32 v58, 0xffffffe0, v58
	s_andn2_b64 vcc, exec, s[52:53]
	v_lshlrev_b32_e32 v32, 1, v32
	s_cbranch_vccnz .LBB0_522
	v_add_u32_e32 v60, v58, v124
	v_ashrrev_i32_e32 v61, 31, v60
	v_lshlrev_b64 v[60:61], 16, v[60:61]
	v_lshl_add_u64 v[60:61], s[10:11], 0, v[60:61]
	v_lshl_add_u64 v[60:61], v[60:61], 0, v[32:33]
	v_mov_b32_e32 v123, v33
	v_lshl_add_u64 v[60:61], v[60:61], 0, v[122:123]
	global_store_dwordx4 v[60:61], v[62:65], off sc1

.LBB0_528:
	v_add_u32_e32 v32, 0x90, v152
	v_mov_b64_e32 v[50:51], s[8:9]
	v_mad_i64_i32 v[50:51], s[52:53], v32, s97, v[50:51]
	v_lshl_add_u64 v[50:51], v[144:145], 1, v[50:51]
	s_and_b64 vcc, exec, s[6:7]
	s_mov_b64 s[52:53], -1
	v_cvt_pk_bf16_f32 v46, v46, v47
	v_cvt_pk_bf16_f32 v47, v48, v49
	v_cvt_pk_bf16_f32 v48, v42, v43
	v_cvt_pk_bf16_f32 v49, v44, v45
	s_cbranch_vccnz .LBB0_530
	s_mov_b64 s[52:53], 0
	global_store_dwordx4 v[50:51], v[46:49], off sc1
.LBB0_530:
	v_lshlrev_b32_e32 v32, 4, v32
	v_and_b32_e32 v32, 0x7df0, v32
	s_andn2_b64 vcc, exec, s[52:53]
	v_lshlrev_b32_e32 v32, 1, v32
	s_cbranch_vccnz .LBB0_532
	v_add_u32_e32 v42, v58, v124
	v_ashrrev_i32_e32 v43, 31, v42
	v_lshlrev_b64 v[42:43], 16, v[42:43]
	v_lshl_add_u64 v[42:43], s[10:11], 0, v[42:43]
	v_lshl_add_u64 v[42:43], v[42:43], 0, v[32:33]
	v_mov_b32_e32 v123, v33
	v_lshl_add_u64 v[42:43], v[42:43], 0, v[122:123]
	global_store_dwordx4 v[42:43], v[46:49], off sc1

.LBB0_538:
	v_add_u32_e32 v32, 0xa0, v152
	v_mov_b64_e32 v[34:35], s[8:9]
	v_mad_i64_i32 v[34:35], s[52:53], v32, s97, v[34:35]
	v_lshl_add_u64 v[34:35], v[144:145], 1, v[34:35]
	s_and_b64 vcc, exec, s[6:7]
	s_mov_b64 s[52:53], -1
	v_cvt_pk_bf16_f32 v28, v28, v29
	v_cvt_pk_bf16_f32 v29, v30, v31
	v_cvt_pk_bf16_f32 v30, v24, v25
	v_cvt_pk_bf16_f32 v31, v26, v27
	s_cbranch_vccnz .LBB0_540
	s_mov_b64 s[52:53], 0
	global_store_dwordx4 v[34:35], v[28:31], off sc1
.LBB0_540:
	v_lshlrev_b32_e32 v24, 4, v32
	v_and_b32_e32 v24, 0x7ef0, v24
	s_andn2_b64 vcc, exec, s[52:53]
	v_lshlrev_b32_e32 v32, 1, v24
	s_cbranch_vccnz .LBB0_542
	v_add_u32_e32 v24, v58, v124
	v_ashrrev_i32_e32 v25, 31, v24
	v_lshlrev_b64 v[24:25], 16, v[24:25]
	v_lshl_add_u64 v[24:25], s[10:11], 0, v[24:25]
	v_lshl_add_u64 v[24:25], v[24:25], 0, v[32:33]
	v_mov_b32_e32 v123, v33
	v_lshl_add_u64 v[24:25], v[24:25], 0, v[122:123]
	global_store_dwordx4 v[24:25], v[28:31], off sc1

.LBB0_548:
	v_add_u32_e32 v18, 0xb0, v152
	v_mov_b64_e32 v[16:17], s[8:9]
	v_mad_i64_i32 v[16:17], s[52:53], v18, s97, v[16:17]
	v_lshl_add_u64 v[16:17], v[144:145], 1, v[16:17]
	s_and_b64 vcc, exec, s[6:7]
	s_mov_b64 s[52:53], -1
	v_cvt_pk_bf16_f32 v12, v12, v13
	v_cvt_pk_bf16_f32 v13, v14, v15
	v_cvt_pk_bf16_f32 v14, v8, v9
	v_cvt_pk_bf16_f32 v15, v10, v11
	s_cbranch_vccnz .LBB0_550
	s_mov_b64 s[52:53], 0
	global_store_dwordx4 v[16:17], v[12:15], off sc1
.LBB0_550:
	v_lshlrev_b32_e32 v8, 4, v18
	v_and_b32_e32 v8, 0x7ff0, v8
	s_andn2_b64 vcc, exec, s[52:53]
	v_lshlrev_b32_e32 v32, 1, v8
	s_cbranch_vccnz .LBB0_552
	v_add_u32_e32 v8, v58, v124
	v_ashrrev_i32_e32 v9, 31, v8
	v_lshlrev_b64 v[8:9], 16, v[8:9]
	v_lshl_add_u64 v[8:9], s[10:11], 0, v[8:9]
	v_lshl_add_u64 v[8:9], v[8:9], 0, v[32:33]
	v_mov_b32_e32 v123, v33
	v_lshl_add_u64 v[8:9], v[8:9], 0, v[122:123]
	global_store_dwordx4 v[8:9], v[12:15], off sc1

.LBB0_559:
	global_store_dwordx4 v[146:147], v[118:121], off offset:256 sc1
	s_cbranch_execnz .LBB0_486
.LBB0_560:
	v_add3_u32 v114, s15, v124, 8
	v_ashrrev_i32_e32 v115, 31, v114
	v_lshlrev_b64 v[114:115], 16, v[114:115]
	v_lshl_add_u64 v[114:115], s[10:11], 0, v[114:115]
	v_lshl_add_u64 v[114:115], v[114:115], 0, v[32:33]
	v_mov_b32_e32 v123, v33
	v_lshl_add_u64 v[114:115], v[114:115], 0, v[122:123]
	global_store_dwordx4 v[114:115], v[118:121], off sc1
	s_and_b64 vcc, exec, s[4:5]
	s_cbranch_vccz .LBB0_487
	s_branch .LBB0_488
.LBB0_561:
	global_store_dwordx4 v[114:115], v[102:105], off offset:256 sc1
	s_cbranch_execnz .LBB0_496
.LBB0_562:
	v_add3_u32 v98, s15, v124, 8
	v_ashrrev_i32_e32 v99, 31, v98
	v_lshlrev_b64 v[98:99], 16, v[98:99]
	v_lshl_add_u64 v[98:99], s[10:11], 0, v[98:99]
	v_lshl_add_u64 v[98:99], v[98:99], 0, v[32:33]
	v_mov_b32_e32 v123, v33
	v_lshl_add_u64 v[98:99], v[98:99], 0, v[122:123]
	global_store_dwordx4 v[98:99], v[102:105], off sc1
	s_and_b64 vcc, exec, s[4:5]
	s_cbranch_vccz .LBB0_497
	s_branch .LBB0_498
.LBB0_563:
	global_store_dwordx4 v[98:99], v[86:89], off offset:256 sc1
	s_cbranch_execnz .LBB0_506
.LBB0_564:
	v_add3_u32 v82, s15, v124, 8
	v_ashrrev_i32_e32 v83, 31, v82
	v_lshlrev_b64 v[82:83], 16, v[82:83]
	v_lshl_add_u64 v[82:83], s[10:11], 0, v[82:83]
	v_lshl_add_u64 v[82:83], v[82:83], 0, v[32:33]
	v_mov_b32_e32 v123, v33
	v_lshl_add_u64 v[82:83], v[82:83], 0, v[122:123]
	global_store_dwordx4 v[82:83], v[86:89], off sc1
	s_and_b64 vcc, exec, s[4:5]
	s_cbranch_vccz .LBB0_507
	s_branch .LBB0_508
.LBB0_565:
	global_store_dwordx4 v[82:83], v[70:73], off offset:256 sc1
	s_cbranch_execnz .LBB0_516
.LBB0_566:
	v_add3_u32 v66, s15, v124, 8
	v_ashrrev_i32_e32 v67, 31, v66
	v_lshlrev_b64 v[66:67], 16, v[66:67]
	v_lshl_add_u64 v[66:67], s[10:11], 0, v[66:67]
	v_lshl_add_u64 v[66:67], v[66:67], 0, v[32:33]
	v_mov_b32_e32 v123, v33
	v_lshl_add_u64 v[66:67], v[66:67], 0, v[122:123]
	global_store_dwordx4 v[66:67], v[70:73], off sc1
	s_and_b64 vcc, exec, s[4:5]
	s_cbranch_vccz .LBB0_517
	s_branch .LBB0_518
.LBB0_567:
	global_store_dwordx4 v[66:67], v[54:57], off offset:256 sc1
	s_cbranch_execnz .LBB0_526
.LBB0_568:
	v_add3_u32 v50, v58, v124, 8
	v_ashrrev_i32_e32 v51, 31, v50
	v_lshlrev_b64 v[50:51], 16, v[50:51]
	v_lshl_add_u64 v[50:51], s[10:11], 0, v[50:51]
	v_lshl_add_u64 v[50:51], v[50:51], 0, v[32:33]
	v_mov_b32_e32 v123, v33
	v_lshl_add_u64 v[50:51], v[50:51], 0, v[122:123]
	global_store_dwordx4 v[50:51], v[54:57], off sc1
	s_and_b64 vcc, exec, s[4:5]
	s_cbranch_vccz .LBB0_527
	s_branch .LBB0_528
.LBB0_569:
	global_store_dwordx4 v[50:51], v[38:41], off offset:256 sc1
	s_cbranch_execnz .LBB0_536
.LBB0_570:
	v_add3_u32 v34, v58, v124, 8
	v_ashrrev_i32_e32 v35, 31, v34
	v_lshlrev_b64 v[34:35], 16, v[34:35]
	v_lshl_add_u64 v[34:35], s[10:11], 0, v[34:35]
	v_lshl_add_u64 v[34:35], v[34:35], 0, v[32:33]
	v_mov_b32_e32 v123, v33
	v_lshl_add_u64 v[34:35], v[34:35], 0, v[122:123]
	global_store_dwordx4 v[34:35], v[38:41], off sc1
	s_and_b64 vcc, exec, s[4:5]
	s_cbranch_vccz .LBB0_537
	s_branch .LBB0_538
.LBB0_571:
	global_store_dwordx4 v[34:35], v[20:23], off offset:256 sc1
	s_cbranch_execnz .LBB0_546
.LBB0_572:
	v_add3_u32 v16, v58, v124, 8
	v_ashrrev_i32_e32 v17, 31, v16
	v_lshlrev_b64 v[16:17], 16, v[16:17]
	v_lshl_add_u64 v[16:17], s[10:11], 0, v[16:17]
	v_lshl_add_u64 v[16:17], v[16:17], 0, v[32:33]
	v_mov_b32_e32 v123, v33
	v_lshl_add_u64 v[16:17], v[16:17], 0, v[122:123]
	global_store_dwordx4 v[16:17], v[20:23], off sc1
	s_and_b64 vcc, exec, s[4:5]
	s_cbranch_vccz .LBB0_547
	s_branch .LBB0_548
.LBB0_573:
	global_store_dwordx4 v[16:17], v[4:7], off offset:256 sc1
	s_cbranch_execnz .LBB0_556
.LBB0_574:
	v_add3_u32 v0, v58, v124, 8
	v_ashrrev_i32_e32 v1, 31, v0
	v_lshlrev_b64 v[0:1], 16, v[0:1]
	v_lshl_add_u64 v[0:1], s[10:11], 0, v[0:1]
	v_lshl_add_u64 v[0:1], v[0:1], 0, v[32:33]
	v_mov_b32_e32 v123, v33
	v_lshl_add_u64 v[0:1], v[0:1], 0, v[122:123]
	global_store_dwordx4 v[0:1], v[4:7], off sc1
	s_andn2_b64 vcc, exec, s[2:3]
	s_mov_b64 s[2:3], -1
	s_cbranch_vccnz .LBB0_467
